# memattn_block: 16 q-norm gain loads issued together (was 8 dependent round trips); score loop issues the 8 K-fragment LDS reads of a key tile together with per-fragment lgkmcnt waits
# baseline (speedup 1.0000x reference)
; #define TIDX launder((int)threadIdx.x)
; DI float bf2f(bf16_t v) { return __uint_as_float(((unsigned)v) << 16); }
; #define LAS __attribute__((address_space(3)))
; DI void memattn_block(const Params& p, int layer, int bh, int tile4) {
;   extern __shared__ __attribute__((aligned(16))) char dyn_lds[];
;   LAS unsigned char* ldsb = (LAS unsigned char*)dyn_lds;
;   const int tid = TIDX, wid = __builtin_amdgcn_readfirstlane(tid >> 6), lane = tid & 63, lr = lane & 31, g = lane >> 5;
;   const int tile = tile4 * 4 + (wid & 3);
;   const int tq = tile * 32 + lr, b = bh >> 2, h = bh & 3;
;   const bf16_t* Kb = (const bf16_t*)(p.ws + A_MEMK) + ((size_t)layer * 8 + bh) * 256 * 128;
;   const bf16_t* VT = (const bf16_t*)(p.ws + A_MEMVT) + ((size_t)layer * 8 + bh) * 128 * 256;
;   LaneKV L; lanekv_init(L, tid, wid);
; #pragma unroll
;   for (int kt = 0; kt < 8; ++kt) kv_issue(ldsb + kt * AT_STAGE, Kb + (size_t)kt * 4096, VT + (size_t)kt * 4096, L);
;   bf16x8 qf[8];
;   if (wid < 4) {
;     const size_t mrow = (size_t)b * T_ + tq;
;     const bf16_t* qp = (const bf16_t*)(p.ws + A_SCR) + mrow * 512 + h * 128 + g * 8;
;     const float* sp8 = (const float*)(p.ws + A_SSP) + SZ_SSP / 4 + mrow * 8;
;     const f32x4 s0 = *(const f32x4*)sp8, s1 = *(const f32x4*)(sp8 + 4);
;     const float rr = rsqrtf((((s0[0] + s0[1]) + (s0[2] + s0[3])) + ((s1[0] + s1[1]) + (s1[2] + s1[3]))) * (1.f / D_) + EPS_);
;     f32x4 qa[8], qb[8]; float ss = 0.f;
; #pragma unroll
;     for (int ks = 0; ks < 8; ++ks) {
;       f32x4 a = (f32x4){0.f, 0.f, 0.f, 0.f}, c = a;
; #pragma unroll
;       for (int sp = 0; sp < 4; ++sp) { const bf16x8 r8 = *(const bf16x8*)(qp + (size_t)sp * M_ * 512 + ks * 16);
; #pragma unroll
;         for (int i = 0; i < 4; ++i) { a[i] += bf2f((bf16_t)r8[i]); c[i] += bf2f((bf16_t)r8[4 + i]); } }
;       a = a * rr; c = c * rr; qa[ks] = a; qb[ks] = c;
.LBB0_104:
	v_mov_b32_e32 v116, v199
	s_ashr_i32 s14, s20, 5
	v_readfirstlane_b32 s12, v116
	s_ashr_i32 s13, s12, 6
	s_lshl_b32 s12, s20, 7
	s_and_b32 s21, s12, 0xf80
	s_lshl_b32 s12, s13, 5
	s_ashr_i32 s15, s14, 31
	s_and_b32 s26, s12, 0x60
	s_ashr_i32 s12, s20, 7
	s_lshl_b64 s[22:23], s[14:15], 16
	s_add_u32 s15, s22, s0
	s_addc_u32 s25, s23, s1
	s_add_u32 s22, s16, s15
	v_ashrrev_i32_e32 v0, 4, v116
	s_addc_u32 s23, s17, s25
	v_lshlrev_b32_e32 v2, 8, v0
	v_xor_b32_e32 v0, v0, v116
	s_add_u32 s24, s18, s15
	v_lshlrev_b32_e32 v0, 4, v0
	s_movk_i32 s15, 0xf0
	s_addc_u32 s25, s19, s25
	v_and_or_b32 v0, v0, s15, v2
	s_lshl_b32 s15, s13, 10
	s_add_i32 s15, s15, 0
	s_mov_b32 m0, s15
	v_lshlrev_b32_e32 v18, 4, v116
	s_waitcnt lgkmcnt(0)
	v_lshl_add_u64 v[2:3], s[22:23], 0, v[0:1]
	v_mov_b32_e32 v19, v1
	global_load_lds_dwordx4 v0, s[22:23]
	s_add_i32 m0, s15, 0x2000
	s_mov_b64 s[22:23], 0x2000
	v_lshl_add_u64 v[4:5], s[24:25], 0, v[18:19]
	global_load_lds_dwordx4 v18, s[24:25]
	v_lshl_add_u64 v[6:7], v[2:3], 0, s[22:23]
	s_add_i32 m0, s15, 0x4000
	v_and_b32_e32 v19, 31, v116
	global_load_lds_dwordx4 v[6:7], off
	v_lshl_add_u64 v[6:7], v[4:5], 0, s[22:23]
	s_add_i32 m0, s15, 0x6000
	s_mov_b64 s[22:23], 0x4000
	global_load_lds_dwordx4 v[6:7], off
	v_lshl_add_u64 v[6:7], v[2:3], 0, s[22:23]
	s_add_i32 m0, s15, 0x8000
	v_bfe_u32 v114, v116, 5, 1
	global_load_lds_dwordx4 v[6:7], off
	v_lshl_add_u64 v[6:7], v[4:5], 0, s[22:23]
	s_add_i32 m0, s15, 0xa000
	s_mov_b64 s[22:23], 0x6000
	global_load_lds_dwordx4 v[6:7], off
	v_lshl_add_u64 v[6:7], v[2:3], 0, s[22:23]
	s_add_i32 m0, s15, 0xc000
	s_nop 0
	global_load_lds_dwordx4 v[6:7], off
	v_lshl_add_u64 v[6:7], v[4:5], 0, s[22:23]
	s_add_i32 m0, s15, 0xe000
	s_mov_b64 s[22:23], 0x8000
	global_load_lds_dwordx4 v[6:7], off
	v_lshl_add_u64 v[6:7], v[2:3], 0, s[22:23]
	s_add_i32 m0, s15, 0x10000
	s_nop 0
	global_load_lds_dwordx4 v[6:7], off
	v_lshl_add_u64 v[6:7], v[4:5], 0, s[22:23]
	s_add_i32 m0, s15, 0x12000
	s_mov_b64 s[22:23], 0xa000
	global_load_lds_dwordx4 v[6:7], off
	v_lshl_add_u64 v[6:7], v[2:3], 0, s[22:23]
	s_add_i32 m0, s15, 0x14000
	s_nop 0
	global_load_lds_dwordx4 v[6:7], off
	v_lshl_add_u64 v[6:7], v[4:5], 0, s[22:23]
	s_add_i32 m0, s15, 0x16000
	s_mov_b64 s[22:23], 0xc000
	global_load_lds_dwordx4 v[6:7], off
	v_lshl_add_u64 v[6:7], v[2:3], 0, s[22:23]
	s_add_i32 m0, s15, 0x18000
	s_nop 0
	global_load_lds_dwordx4 v[6:7], off
	v_lshl_add_u64 v[6:7], v[4:5], 0, s[22:23]
	s_add_i32 m0, s15, 0x1a000
	s_mov_b64 s[22:23], 0xe000
	global_load_lds_dwordx4 v[6:7], off
	v_lshl_add_u64 v[2:3], v[2:3], 0, s[22:23]
	s_add_i32 m0, s15, 0x1c000
	s_nop 0
	global_load_lds_dwordx4 v[2:3], off
	v_lshl_add_u64 v[2:3], v[4:5], 0, s[22:23]
	s_add_i32 m0, s15, 0x1e000
	s_or_b32 s22, s21, s26
	global_load_lds_dwordx4 v[2:3], off
	s_and_b32 s21, s14, 3
	s_cmp_lt_i32 s13, 4
	s_cselect_b64 s[14:15], -1, 0
	s_cmp_gt_i32 s13, 3
	v_or_b32_e32 v115, s22, v19
	s_cbranch_scc1 .LBB0_106
	s_ashr_i32 s13, s12, 31
	s_lshl_b64 s[22:23], s[12:13], 12
	v_or_b32_e32 v2, s22, v115
	v_mov_b32_e32 v3, s23
	v_lshlrev_b64 v[4:5], 10, v[2:3]
	v_readlane_b32 s22, v253, 10
	v_lshl_add_u64 v[4:5], s[4:5], 0, v[4:5]
	v_readlane_b32 s23, v253, 11
	s_lshl_b32 s22, s21, 8
	v_lshlrev_b32_e32 v6, 4, v114
	v_lshl_add_u64 v[4:5], v[4:5], 0, s[22:23]
	v_mov_b32_e32 v7, v1
	v_lshlrev_b64 v[2:3], 5, v[2:3]
	v_lshl_add_u64 v[36:37], v[4:5], 0, v[6:7]
	v_lshl_add_u64 v[6:7], s[6:7], 0, v[2:3]
	global_load_dwordx4 v[2:5], v[6:7], off
	s_nop 0
	global_load_dwordx4 v[6:9], v[6:7], off offset:16
	s_mov_b32 s22, 0x800000
	s_mov_b32 s13, s23
	v_writelane_b32 v253, s12, 10
	s_mov_b32 s84, 0x800000
	s_waitcnt vmcnt(0)
	v_mov_b32_e32 v10, v2
	v_mov_b32_e32 v11, v6
	v_mov_b32_e32 v6, v3
	v_pk_add_f32 v[2:3], v[10:11], v[6:7]
	v_mov_b32_e32 v6, v4
	v_mov_b32_e32 v7, v8
	v_mov_b32_e32 v8, v5
	v_pk_add_f32 v[4:5], v[6:7], v[8:9]
	v_writelane_b32 v253, s13, 11
	v_pk_add_f32 v[2:3], v[2:3], v[4:5]
	s_mov_b32 s13, 0x1000000
	v_add_f32_e32 v0, v2, v3
	v_fmamk_f32 v0, v0, 0x3a000000, v249
	v_cmp_gt_f32_e32 vcc, s22, v0
	v_mul_f32_e32 v2, 0x4b800000, v0
	s_nop 0
	v_cndmask_b32_e32 v0, v0, v2, vcc
	v_rsq_f32_e32 v0, v0
	s_nop 0
	v_mul_f32_e32 v2, 0x45800000, v0
	v_cndmask_b32_e32 v0, v0, v2, vcc
	v_add_co_u32_e32 v42, vcc, s22, v36
	global_load_dwordx4 v[2:5], v[36:37], off
	s_nop 0
	v_addc_co_u32_e32 v43, vcc, 0, v37, vcc
	v_add_co_u32_e32 v40, vcc, s13, v36
	s_mov_b32 s13, 0x1800000
	s_nop 0
	v_addc_co_u32_e32 v41, vcc, 0, v37, vcc
	global_load_dwordx4 v[6:9], v[42:43], off
	global_load_dwordx4 v[10:13], v[40:41], off
	v_add_co_u32_e32 v38, vcc, s13, v36
	s_waitcnt vmcnt(0)
	v_and_b32_e32 v23, 0xffff0000, v6
	v_addc_co_u32_e32 v39, vcc, 0, v37, vcc
	global_load_dwordx4 v[14:17], v[38:39], off
	v_and_b32_e32 v21, 0xffff0000, v2
	v_lshlrev_b32_e32 v20, 16, v2
	v_pk_add_f32 v[20:21], v[20:21], 0 op_sel_hi:[1,0]
	v_lshlrev_b32_e32 v22, 16, v6
	v_pk_add_f32 v[20:21], v[20:21], v[22:23]
	v_and_b32_e32 v23, 0xffff0000, v10
	v_lshlrev_b32_e32 v22, 16, v10
	v_pk_add_f32 v[20:21], v[20:21], v[22:23]
	v_and_b32_e32 v25, 0xffff0000, v8
	v_lshlrev_b32_e32 v24, 16, v8
	v_lshlrev_b32_e32 v6, 16, v11
	s_waitcnt vmcnt(0)
; DI float bf2f(bf16_t v) { return __uint_as_float(((unsigned)v) << 16); }
; DI void memattn_block(const Params& p, int layer, int bh, int tile4) {
;     ...
;     for (int ks = 0; ks < 8; ++ks) {
;       f32x4 a = (f32x4){0.f, 0.f, 0.f, 0.f}, c = a;
; #pragma unroll
;       for (int sp = 0; sp < 4; ++sp) { const bf16x8 r8 = *(const bf16x8*)(qp + (size_t)sp * M_ * 512 + ks * 16);
; #pragma unroll
;         for (int i = 0; i < 4; ++i) { a[i] += bf2f((bf16_t)r8[i]); c[i] += bf2f((bf16_t)r8[4 + i]); } }
;       a = a * rr; c = c * rr; qa[ks] = a; qb[ks] = c;
;       ss += (a[0] * a[0] + a[1] * a[1]) + (a[2] * a[2] + a[3] * a[3]) + (c[0] * c[0] + c[1] * c[1]) + (c[2] * c[2] + c[3] * c[3]);
	v_and_b32_e32 v23, 0xffff0000, v14
	v_lshlrev_b32_e32 v22, 16, v14
	v_pk_add_f32 v[22:23], v[20:21], v[22:23]
	v_and_b32_e32 v21, 0xffff0000, v4
	v_lshlrev_b32_e32 v20, 16, v4
	v_pk_add_f32 v[20:21], v[20:21], 0 op_sel_hi:[1,0]
	s_nop 0
	v_pk_add_f32 v[20:21], v[20:21], v[24:25]
	v_and_b32_e32 v25, 0xffff0000, v12
	v_lshlrev_b32_e32 v24, 16, v12
	v_pk_add_f32 v[20:21], v[20:21], v[24:25]
	v_and_b32_e32 v25, 0xffff0000, v16
	v_lshlrev_b32_e32 v24, 16, v16
	v_pk_add_f32 v[26:27], v[20:21], v[24:25]
	v_and_b32_e32 v21, 0xffff0000, v3
	v_lshlrev_b32_e32 v20, 16, v3
	v_pk_add_f32 v[2:3], v[20:21], 0 op_sel_hi:[1,0]
	v_and_b32_e32 v21, 0xffff0000, v7
	v_lshlrev_b32_e32 v20, 16, v7
	v_pk_add_f32 v[2:3], v[2:3], v[20:21]
	v_and_b32_e32 v7, 0xffff0000, v11
	v_pk_add_f32 v[2:3], v[2:3], v[6:7]
	v_and_b32_e32 v7, 0xffff0000, v15
	v_lshlrev_b32_e32 v6, 16, v15
	v_pk_add_f32 v[2:3], v[2:3], v[6:7]
	v_and_b32_e32 v7, 0xffff0000, v5
	v_lshlrev_b32_e32 v6, 16, v5
	v_pk_add_f32 v[4:5], v[6:7], 0 op_sel_hi:[1,0]
	v_and_b32_e32 v7, 0xffff0000, v9
	v_lshlrev_b32_e32 v6, 16, v9
	v_pk_add_f32 v[4:5], v[4:5], v[6:7]
	v_and_b32_e32 v7, 0xffff0000, v13
	v_lshlrev_b32_e32 v6, 16, v13
	v_pk_add_f32 v[4:5], v[4:5], v[6:7]
	v_and_b32_e32 v7, 0xffff0000, v17
	v_lshlrev_b32_e32 v6, 16, v17
	v_pk_add_f32 v[4:5], v[4:5], v[6:7]
	v_pk_mul_f32 v[20:21], v[0:1], v[2:3] op_sel_hi:[0,1]
	v_pk_mul_f32 v[24:25], v[0:1], v[22:23] op_sel_hi:[0,1]
	v_pk_mul_f32 v[22:23], v[0:1], v[4:5] op_sel_hi:[0,1]
	global_load_dwordx4 v[14:17], v[36:37], off offset:32
	global_load_dwordx4 v[10:13], v[42:43], off offset:32
	global_load_dwordx4 v[6:9], v[40:41], off offset:32
	global_load_dwordx4 v[2:5], v[38:39], off offset:32
	v_pk_mul_f32 v[26:27], v[0:1], v[26:27] op_sel_hi:[0,1]
	s_waitcnt vmcnt(0)
	v_and_b32_e32 v29, 0xffff0000, v14
	v_lshlrev_b32_e32 v28, 16, v14
	v_pk_add_f32 v[28:29], v[28:29], 0 op_sel_hi:[1,0]
	v_and_b32_e32 v31, 0xffff0000, v10
	v_lshlrev_b32_e32 v30, 16, v10
	v_pk_add_f32 v[28:29], v[28:29], v[30:31]
	v_and_b32_e32 v31, 0xffff0000, v6
	v_lshlrev_b32_e32 v30, 16, v6
	v_pk_add_f32 v[28:29], v[28:29], v[30:31]
	v_and_b32_e32 v31, 0xffff0000, v2
	v_lshlrev_b32_e32 v30, 16, v2
	v_pk_add_f32 v[30:31], v[28:29], v[30:31]
	v_and_b32_e32 v29, 0xffff0000, v16
	v_lshlrev_b32_e32 v28, 16, v16
	v_pk_add_f32 v[28:29], v[28:29], 0 op_sel_hi:[1,0]
	v_and_b32_e32 v33, 0xffff0000, v12
	v_lshlrev_b32_e32 v32, 16, v12
	v_pk_add_f32 v[28:29], v[28:29], v[32:33]
	v_and_b32_e32 v33, 0xffff0000, v8
	v_lshlrev_b32_e32 v32, 16, v8
	v_pk_add_f32 v[28:29], v[28:29], v[32:33]
	v_and_b32_e32 v33, 0xffff0000, v4
	v_lshlrev_b32_e32 v32, 16, v4
	v_pk_add_f32 v[34:35], v[28:29], v[32:33]
	v_and_b32_e32 v29, 0xffff0000, v15
	v_lshlrev_b32_e32 v28, 16, v15
	v_pk_add_f32 v[14:15], v[28:29], 0 op_sel_hi:[1,0]
	v_and_b32_e32 v29, 0xffff0000, v11
	v_lshlrev_b32_e32 v28, 16, v11
	v_pk_add_f32 v[10:11], v[14:15], v[28:29]
	v_and_b32_e32 v15, 0xffff0000, v7
	v_lshlrev_b32_e32 v14, 16, v7
	v_pk_add_f32 v[6:7], v[10:11], v[14:15]
	v_and_b32_e32 v11, 0xffff0000, v3
	v_lshlrev_b32_e32 v10, 16, v3
	v_pk_add_f32 v[2:3], v[6:7], v[10:11]
	v_and_b32_e32 v7, 0xffff0000, v17
	v_lshlrev_b32_e32 v6, 16, v17
	v_pk_add_f32 v[6:7], v[6:7], 0 op_sel_hi:[1,0]
	v_and_b32_e32 v11, 0xffff0000, v13
	v_lshlrev_b32_e32 v10, 16, v13
	v_pk_add_f32 v[6:7], v[6:7], v[10:11]
	v_and_b32_e32 v11, 0xffff0000, v9
	v_lshlrev_b32_e32 v10, 16, v9
	v_pk_add_f32 v[6:7], v[6:7], v[10:11]
	v_and_b32_e32 v9, 0xffff0000, v5
	v_lshlrev_b32_e32 v8, 16, v5
	v_pk_add_f32 v[4:5], v[6:7], v[8:9]
	v_pk_mul_f32 v[32:33], v[0:1], v[30:31] op_sel_hi:[0,1]
	v_pk_mul_f32 v[28:29], v[0:1], v[2:3] op_sel_hi:[0,1]
	v_pk_mul_f32 v[30:31], v[0:1], v[4:5] op_sel_hi:[0,1]
	v_mov_b32_e32 v4, v25
	v_mov_b32_e32 v5, v33
	v_mov_b32_e32 v2, v24
	v_mov_b32_e32 v3, v32
	v_pk_mul_f32 v[4:5], v[4:5], v[4:5]
	v_mov_b32_e32 v6, v21
	v_mov_b32_e32 v7, v29
	v_pk_mul_f32 v[34:35], v[0:1], v[34:35] op_sel_hi:[0,1]
	v_pk_fma_f32 v[2:3], v[2:3], v[2:3], v[4:5]
	v_mov_b32_e32 v4, v20
	v_mov_b32_e32 v5, v28
	v_pk_mul_f32 v[6:7], v[6:7], v[6:7]
	s_nop 0
	v_pk_fma_f32 v[4:5], v[4:5], v[4:5], v[6:7]
	v_mov_b32_e32 v6, v27
	v_mov_b32_e32 v7, v35
	v_pk_add_f32 v[2:3], v[2:3], v[4:5]
	v_mov_b32_e32 v4, v26
	v_mov_b32_e32 v5, v34
	v_pk_mul_f32 v[6:7], v[6:7], v[6:7]
	s_nop 0
	v_pk_fma_f32 v[4:5], v[4:5], v[4:5], v[6:7]
	v_mov_b32_e32 v6, v23
	v_mov_b32_e32 v7, v31
	v_pk_add_f32 v[2:3], v[4:5], v[2:3]
	v_mov_b32_e32 v4, v22
	v_mov_b32_e32 v5, v30
	v_pk_mul_f32 v[6:7], v[6:7], v[6:7]
	s_nop 0
	v_pk_fma_f32 v[4:5], v[4:5], v[4:5], v[6:7]
	s_nop 0
	v_pk_add_f32 v[2:3], v[4:5], v[2:3]
	global_load_dwordx4 v[4:7], v[36:37], off offset:64
	global_load_dwordx4 v[8:11], v[42:43], off offset:64
	global_load_dwordx4 v[12:15], v[40:41], off offset:64
	global_load_dwordx4 v[44:47], v[38:39], off offset:64
	v_pk_add_f32 v[2:3], v[2:3], v[2:3] op_sel:[0,1] op_sel_hi:[1,0]
	s_waitcnt vmcnt(0)
; DI float bf2f(bf16_t v) { return __uint_as_float(((unsigned)v) << 16); }
; DI void memattn_block(const Params& p, int layer, int bh, int tile4) {
;     ...
;     for (int ks = 0; ks < 8; ++ks) {
;       f32x4 a = (f32x4){0.f, 0.f, 0.f, 0.f}, c = a;
; #pragma unroll
;       for (int sp = 0; sp < 4; ++sp) { const bf16x8 r8 = *(const bf16x8*)(qp + (size_t)sp * M_ * 512 + ks * 16);
; #pragma unroll
;         for (int i = 0; i < 4; ++i) { a[i] += bf2f((bf16_t)r8[i]); c[i] += bf2f((bf16_t)r8[4 + i]); } }
;       a = a * rr; c = c * rr; qa[ks] = a; qb[ks] = c;
;       ss += (a[0] * a[0] + a[1] * a[1]) + (a[2] * a[2] + a[3] * a[3]) + (c[0] * c[0] + c[1] * c[1]) + (c[2] * c[2] + c[3] * c[3]);
	v_and_b32_e32 v17, 0xffff0000, v4
	v_lshlrev_b32_e32 v16, 16, v4
	v_pk_add_f32 v[16:17], v[16:17], 0 op_sel_hi:[1,0]
	v_and_b32_e32 v49, 0xffff0000, v8
	v_lshlrev_b32_e32 v48, 16, v8
	v_pk_add_f32 v[16:17], v[16:17], v[48:49]
	v_and_b32_e32 v49, 0xffff0000, v12
	v_lshlrev_b32_e32 v48, 16, v12
	v_pk_add_f32 v[16:17], v[16:17], v[48:49]
	v_and_b32_e32 v49, 0xffff0000, v44
	v_lshlrev_b32_e32 v48, 16, v44
	v_pk_add_f32 v[16:17], v[16:17], v[48:49]
	v_and_b32_e32 v49, 0xffff0000, v6
	v_lshlrev_b32_e32 v48, 16, v6
	v_pk_add_f32 v[48:49], v[48:49], 0 op_sel_hi:[1,0]
	v_and_b32_e32 v51, 0xffff0000, v10
	v_lshlrev_b32_e32 v50, 16, v10
	v_pk_add_f32 v[48:49], v[48:49], v[50:51]
	v_and_b32_e32 v51, 0xffff0000, v14
	v_lshlrev_b32_e32 v50, 16, v14
	v_pk_add_f32 v[48:49], v[48:49], v[50:51]
	v_and_b32_e32 v51, 0xffff0000, v46
	v_lshlrev_b32_e32 v50, 16, v46
	v_pk_add_f32 v[50:51], v[48:49], v[50:51]
	v_and_b32_e32 v49, 0xffff0000, v5
	v_lshlrev_b32_e32 v48, 16, v5
	v_pk_add_f32 v[4:5], v[48:49], 0 op_sel_hi:[1,0]
	v_and_b32_e32 v49, 0xffff0000, v9
	v_lshlrev_b32_e32 v48, 16, v9
	v_pk_add_f32 v[4:5], v[4:5], v[48:49]
	v_and_b32_e32 v9, 0xffff0000, v13
	v_lshlrev_b32_e32 v8, 16, v13
	v_pk_add_f32 v[4:5], v[4:5], v[8:9]
	v_and_b32_e32 v9, 0xffff0000, v45
	v_lshlrev_b32_e32 v8, 16, v45
	v_pk_add_f32 v[4:5], v[4:5], v[8:9]
	v_and_b32_e32 v9, 0xffff0000, v7
	v_lshlrev_b32_e32 v8, 16, v7
	v_pk_add_f32 v[6:7], v[8:9], 0 op_sel_hi:[1,0]
	v_and_b32_e32 v9, 0xffff0000, v11
	v_lshlrev_b32_e32 v8, 16, v11
	v_pk_add_f32 v[6:7], v[6:7], v[8:9]
	v_and_b32_e32 v9, 0xffff0000, v15
	v_lshlrev_b32_e32 v8, 16, v15
	v_pk_add_f32 v[6:7], v[6:7], v[8:9]
	v_and_b32_e32 v9, 0xffff0000, v47
	v_lshlrev_b32_e32 v8, 16, v47
	v_pk_add_f32 v[6:7], v[6:7], v[8:9]
	v_pk_mul_f32 v[48:49], v[0:1], v[16:17] op_sel_hi:[0,1]
	v_pk_mul_f32 v[44:45], v[0:1], v[4:5] op_sel_hi:[0,1]
	v_pk_mul_f32 v[46:47], v[0:1], v[6:7] op_sel_hi:[0,1]
	v_pk_mul_f32 v[4:5], v[44:45], v[44:45]
	v_pk_mul_f32 v[6:7], v[48:49], v[48:49]
	v_pk_mul_f32 v[50:51], v[0:1], v[50:51] op_sel_hi:[0,1]
	v_pk_mov_b32 v[8:9], v[6:7], v[4:5] op_sel:[1,0]
	v_mov_b32_e32 v7, v5
	v_pk_add_f32 v[4:5], v[8:9], v[6:7]
	v_pk_mul_f32 v[6:7], v[46:47], v[46:47]
	v_pk_mul_f32 v[8:9], v[50:51], v[50:51]
	v_mov_b32_e32 v10, v6
	v_mov_b32_e32 v11, v8
	v_mov_b32_e32 v8, v7
	v_pk_add_f32 v[4:5], v[4:5], v[4:5] op_sel:[0,1] op_sel_hi:[1,0]
	v_pk_add_f32 v[6:7], v[10:11], v[8:9]
	s_nop 0
	v_pk_add_f32 v[4:5], v[6:7], v[4:5] op_sel:[1,0] op_sel_hi:[0,1]
	v_pk_add_f32 v[4:5], v[6:7], v[4:5]
	global_load_dwordx4 v[6:9], v[36:37], off offset:96
	global_load_dwordx4 v[10:13], v[42:43], off offset:96
	global_load_dwordx4 v[14:17], v[40:41], off offset:96
	global_load_dwordx4 v[52:55], v[38:39], off offset:96
	s_waitcnt vmcnt(0)
	v_and_b32_e32 v57, 0xffff0000, v6
	v_lshlrev_b32_e32 v56, 16, v6
	v_pk_add_f32 v[56:57], v[56:57], 0 op_sel_hi:[1,0]
	v_and_b32_e32 v59, 0xffff0000, v10
	v_lshlrev_b32_e32 v58, 16, v10
	v_pk_add_f32 v[56:57], v[56:57], v[58:59]
	v_and_b32_e32 v59, 0xffff0000, v14
	v_lshlrev_b32_e32 v58, 16, v14
	v_pk_add_f32 v[56:57], v[56:57], v[58:59]
	v_and_b32_e32 v59, 0xffff0000, v52
	v_lshlrev_b32_e32 v58, 16, v52
	v_pk_add_f32 v[56:57], v[56:57], v[58:59]
	v_and_b32_e32 v59, 0xffff0000, v8
	v_lshlrev_b32_e32 v58, 16, v8
	v_pk_add_f32 v[58:59], v[58:59], 0 op_sel_hi:[1,0]
	v_and_b32_e32 v61, 0xffff0000, v12
	v_lshlrev_b32_e32 v60, 16, v12
	v_pk_add_f32 v[58:59], v[58:59], v[60:61]
	v_and_b32_e32 v61, 0xffff0000, v16
	v_lshlrev_b32_e32 v60, 16, v16
	v_pk_add_f32 v[58:59], v[58:59], v[60:61]
	v_and_b32_e32 v61, 0xffff0000, v54
	v_lshlrev_b32_e32 v60, 16, v54
	v_pk_add_f32 v[58:59], v[58:59], v[60:61]
	v_and_b32_e32 v61, 0xffff0000, v7
	v_lshlrev_b32_e32 v60, 16, v7
	v_pk_add_f32 v[6:7], v[60:61], 0 op_sel_hi:[1,0]
	v_and_b32_e32 v61, 0xffff0000, v11
	v_lshlrev_b32_e32 v60, 16, v11
	v_pk_add_f32 v[6:7], v[6:7], v[60:61]
	v_and_b32_e32 v11, 0xffff0000, v15
	v_lshlrev_b32_e32 v10, 16, v15
	v_pk_add_f32 v[6:7], v[6:7], v[10:11]
	v_and_b32_e32 v11, 0xffff0000, v53
	v_lshlrev_b32_e32 v10, 16, v53
	v_pk_add_f32 v[6:7], v[6:7], v[10:11]
	v_and_b32_e32 v11, 0xffff0000, v9
	v_lshlrev_b32_e32 v10, 16, v9
	v_pk_add_f32 v[8:9], v[10:11], 0 op_sel_hi:[1,0]
	v_and_b32_e32 v11, 0xffff0000, v13
	v_lshlrev_b32_e32 v10, 16, v13
	v_pk_add_f32 v[8:9], v[8:9], v[10:11]
	v_and_b32_e32 v11, 0xffff0000, v17
	v_lshlrev_b32_e32 v10, 16, v17
	v_pk_add_f32 v[8:9], v[8:9], v[10:11]
	v_and_b32_e32 v11, 0xffff0000, v55
	v_lshlrev_b32_e32 v10, 16, v55
	v_pk_add_f32 v[8:9], v[8:9], v[10:11]
	v_pk_mul_f32 v[52:53], v[0:1], v[6:7] op_sel_hi:[0,1]
	v_pk_mul_f32 v[54:55], v[0:1], v[8:9] op_sel_hi:[0,1]
	global_load_dwordx4 v[6:9], v[36:37], off offset:128
	global_load_dwordx4 v[10:13], v[42:43], off offset:128
	global_load_dwordx4 v[14:17], v[40:41], off offset:128
	global_load_dwordx4 v[60:63], v[38:39], off offset:128
	v_pk_mul_f32 v[58:59], v[0:1], v[58:59] op_sel_hi:[0,1]
	v_pk_mul_f32 v[56:57], v[0:1], v[56:57] op_sel_hi:[0,1]
	s_waitcnt vmcnt(0)
; DI float bf2f(bf16_t v) { return __uint_as_float(((unsigned)v) << 16); }
; DI void memattn_block(const Params& p, int layer, int bh, int tile4) {
;     ...
;     for (int ks = 0; ks < 8; ++ks) {
;       f32x4 a = (f32x4){0.f, 0.f, 0.f, 0.f}, c = a;
; #pragma unroll
;       for (int sp = 0; sp < 4; ++sp) { const bf16x8 r8 = *(const bf16x8*)(qp + (size_t)sp * M_ * 512 + ks * 16);
; #pragma unroll
;         for (int i = 0; i < 4; ++i) { a[i] += bf2f((bf16_t)r8[i]); c[i] += bf2f((bf16_t)r8[4 + i]); } }
;       a = a * rr; c = c * rr; qa[ks] = a; qb[ks] = c;
;       ss += (a[0] * a[0] + a[1] * a[1]) + (a[2] * a[2] + a[3] * a[3]) + (c[0] * c[0] + c[1] * c[1]) + (c[2] * c[2] + c[3] * c[3]);
	v_and_b32_e32 v65, 0xffff0000, v6
	v_lshlrev_b32_e32 v64, 16, v6
	v_pk_add_f32 v[64:65], v[64:65], 0 op_sel_hi:[1,0]
	v_and_b32_e32 v67, 0xffff0000, v10
	v_lshlrev_b32_e32 v66, 16, v10
	v_pk_add_f32 v[64:65], v[64:65], v[66:67]
	v_and_b32_e32 v67, 0xffff0000, v14
	v_lshlrev_b32_e32 v66, 16, v14
	v_pk_add_f32 v[64:65], v[64:65], v[66:67]
	v_and_b32_e32 v67, 0xffff0000, v60
	v_lshlrev_b32_e32 v66, 16, v60
	v_pk_add_f32 v[64:65], v[64:65], v[66:67]
	v_and_b32_e32 v67, 0xffff0000, v8
	v_lshlrev_b32_e32 v66, 16, v8
	v_pk_add_f32 v[66:67], v[66:67], 0 op_sel_hi:[1,0]
	v_and_b32_e32 v69, 0xffff0000, v12
	v_lshlrev_b32_e32 v68, 16, v12
	v_pk_add_f32 v[66:67], v[66:67], v[68:69]
	v_and_b32_e32 v69, 0xffff0000, v16
	v_lshlrev_b32_e32 v68, 16, v16
	v_pk_add_f32 v[66:67], v[66:67], v[68:69]
	v_and_b32_e32 v69, 0xffff0000, v62
	v_lshlrev_b32_e32 v68, 16, v62
	v_pk_add_f32 v[66:67], v[66:67], v[68:69]
	v_and_b32_e32 v69, 0xffff0000, v7
	v_lshlrev_b32_e32 v68, 16, v7
	v_pk_add_f32 v[6:7], v[68:69], 0 op_sel_hi:[1,0]
	v_and_b32_e32 v69, 0xffff0000, v11
	v_lshlrev_b32_e32 v68, 16, v11
	v_pk_add_f32 v[6:7], v[6:7], v[68:69]
	v_and_b32_e32 v11, 0xffff0000, v15
	v_lshlrev_b32_e32 v10, 16, v15
	v_pk_add_f32 v[6:7], v[6:7], v[10:11]
	v_and_b32_e32 v11, 0xffff0000, v61
	v_lshlrev_b32_e32 v10, 16, v61
	v_pk_add_f32 v[6:7], v[6:7], v[10:11]
	v_and_b32_e32 v11, 0xffff0000, v9
	v_lshlrev_b32_e32 v10, 16, v9
	v_pk_add_f32 v[8:9], v[10:11], 0 op_sel_hi:[1,0]
	v_and_b32_e32 v11, 0xffff0000, v13
	v_lshlrev_b32_e32 v10, 16, v13
	v_pk_add_f32 v[8:9], v[8:9], v[10:11]
	v_and_b32_e32 v11, 0xffff0000, v17
	v_lshlrev_b32_e32 v10, 16, v17
	v_pk_add_f32 v[8:9], v[8:9], v[10:11]
	v_and_b32_e32 v11, 0xffff0000, v63
	v_lshlrev_b32_e32 v10, 16, v63
	v_pk_add_f32 v[8:9], v[8:9], v[10:11]
	v_pk_mul_f32 v[64:65], v[0:1], v[64:65] op_sel_hi:[0,1]
	v_pk_mul_f32 v[62:63], v[0:1], v[8:9] op_sel_hi:[0,1]
	v_mov_b32_e32 v8, v59
	v_mov_b32_e32 v9, v65
	v_pk_mul_f32 v[60:61], v[0:1], v[6:7] op_sel_hi:[0,1]
	v_mov_b32_e32 v6, v58
	v_mov_b32_e32 v7, v64
	v_pk_mul_f32 v[8:9], v[8:9], v[8:9]
	v_mul_f32_e32 v10, v60, v60
	v_pk_fma_f32 v[6:7], v[6:7], v[6:7], v[8:9]
	v_mul_f32_e32 v8, v57, v57
	v_pk_fma_f32 v[8:9], v[56:57], v[56:57], v[8:9] op_sel_hi:[1,1,0]
	v_mul_f32_e32 v12, v61, v61
	v_mov_b32_e32 v9, v10
	v_mul_f32_e32 v10, v53, v53
	v_pk_fma_f32 v[10:11], v[52:53], v[52:53], v[10:11] op_sel_hi:[1,1,0]
	v_pk_mul_f32 v[66:67], v[0:1], v[66:67] op_sel_hi:[0,1]
	v_mov_b32_e32 v11, v12
	v_pk_add_f32 v[8:9], v[8:9], v[10:11]
	v_mov_b32_e32 v10, v55
	v_mov_b32_e32 v11, v67
	v_mul_f32_e32 v13, v62, v62
	v_pk_add_f32 v[6:7], v[6:7], v[8:9]
	v_mov_b32_e32 v8, v54
	v_mov_b32_e32 v9, v66
	v_pk_mul_f32 v[10:11], v[10:11], v[10:11]
	v_mul_f32_e32 v5, v63, v63
	v_pk_fma_f32 v[8:9], v[8:9], v[8:9], v[10:11]
	v_mov_b32_e32 v3, v13
	v_pk_add_f32 v[6:7], v[8:9], v[6:7]
	v_pk_add_f32 v[2:3], v[2:3], v[4:5]
	s_nop 0
	v_pk_add_f32 v[76:77], v[2:3], v[6:7]
	global_load_dwordx4 v[2:5], v[36:37], off offset:160
	global_load_dwordx4 v[6:9], v[42:43], off offset:160
	global_load_dwordx4 v[10:13], v[40:41], off offset:160
	global_load_dwordx4 v[14:17], v[38:39], off offset:160
	s_waitcnt vmcnt(0)
	v_and_b32_e32 v69, 0xffff0000, v2
	v_lshlrev_b32_e32 v68, 16, v2
	v_pk_add_f32 v[68:69], v[68:69], 0 op_sel_hi:[1,0]
	v_and_b32_e32 v71, 0xffff0000, v6
	v_lshlrev_b32_e32 v70, 16, v6
	v_pk_add_f32 v[68:69], v[68:69], v[70:71]
	v_and_b32_e32 v71, 0xffff0000, v10
	v_lshlrev_b32_e32 v70, 16, v10
	v_pk_add_f32 v[68:69], v[68:69], v[70:71]
	v_and_b32_e32 v71, 0xffff0000, v14
	v_lshlrev_b32_e32 v70, 16, v14
	v_pk_add_f32 v[68:69], v[68:69], v[70:71]
	v_and_b32_e32 v71, 0xffff0000, v4
	v_lshlrev_b32_e32 v70, 16, v4
	v_pk_add_f32 v[70:71], v[70:71], 0 op_sel_hi:[1,0]
	v_and_b32_e32 v73, 0xffff0000, v8
	v_lshlrev_b32_e32 v72, 16, v8
	v_pk_add_f32 v[70:71], v[70:71], v[72:73]
	v_and_b32_e32 v73, 0xffff0000, v12
	v_lshlrev_b32_e32 v72, 16, v12
	v_pk_add_f32 v[70:71], v[70:71], v[72:73]
	v_and_b32_e32 v73, 0xffff0000, v16
	v_lshlrev_b32_e32 v72, 16, v16
	v_pk_add_f32 v[70:71], v[70:71], v[72:73]
	v_and_b32_e32 v73, 0xffff0000, v3
	v_lshlrev_b32_e32 v72, 16, v3
	v_pk_add_f32 v[2:3], v[72:73], 0 op_sel_hi:[1,0]
	v_and_b32_e32 v73, 0xffff0000, v7
	v_lshlrev_b32_e32 v72, 16, v7
	v_pk_add_f32 v[2:3], v[2:3], v[72:73]
	v_and_b32_e32 v7, 0xffff0000, v11
	v_lshlrev_b32_e32 v6, 16, v11
	v_pk_add_f32 v[2:3], v[2:3], v[6:7]
	v_and_b32_e32 v7, 0xffff0000, v15
	v_lshlrev_b32_e32 v6, 16, v15
	v_pk_add_f32 v[2:3], v[2:3], v[6:7]
	v_and_b32_e32 v7, 0xffff0000, v5
	v_lshlrev_b32_e32 v6, 16, v5
	v_pk_add_f32 v[4:5], v[6:7], 0 op_sel_hi:[1,0]
	v_and_b32_e32 v7, 0xffff0000, v9
	v_lshlrev_b32_e32 v6, 16, v9
	v_pk_add_f32 v[4:5], v[4:5], v[6:7]
	v_and_b32_e32 v7, 0xffff0000, v13
	v_lshlrev_b32_e32 v6, 16, v13
	v_pk_add_f32 v[4:5], v[4:5], v[6:7]
	v_and_b32_e32 v7, 0xffff0000, v17
	v_lshlrev_b32_e32 v6, 16, v17
	v_pk_add_f32 v[4:5], v[4:5], v[6:7]
	v_pk_mul_f32 v[72:73], v[0:1], v[68:69] op_sel_hi:[0,1]
	v_pk_mul_f32 v[68:69], v[0:1], v[2:3] op_sel_hi:[0,1]
	v_pk_mul_f32 v[74:75], v[0:1], v[70:71] op_sel_hi:[0,1]
	v_pk_mul_f32 v[70:71], v[0:1], v[4:5] op_sel_hi:[0,1]
	v_pk_mul_f32 v[2:3], v[68:69], v[68:69]
	v_pk_mul_f32 v[4:5], v[72:73], v[72:73]
	s_nop 0
	v_pk_mov_b32 v[6:7], v[4:5], v[2:3] op_sel:[1,0]
	v_mov_b32_e32 v5, v3
	v_pk_add_f32 v[2:3], v[6:7], v[4:5]
	v_pk_mul_f32 v[4:5], v[70:71], v[70:71]
	v_pk_mul_f32 v[6:7], v[74:75], v[74:75]
	v_mov_b32_e32 v8, v4
	v_mov_b32_e32 v9, v6
	v_mov_b32_e32 v6, v5
	v_pk_add_f32 v[2:3], v[2:3], v[2:3] op_sel:[0,1] op_sel_hi:[1,0]
	v_pk_add_f32 v[4:5], v[8:9], v[6:7]
	s_nop 0
	v_pk_add_f32 v[2:3], v[4:5], v[2:3] op_sel:[1,0] op_sel_hi:[0,1]
	v_pk_add_f32 v[82:83], v[4:5], v[2:3]
	global_load_dwordx4 v[2:5], v[36:37], off offset:192
	global_load_dwordx4 v[6:9], v[42:43], off offset:192
	global_load_dwordx4 v[10:13], v[40:41], off offset:192
	global_load_dwordx4 v[14:17], v[38:39], off offset:192
	s_waitcnt vmcnt(0)
; DI float bf2f(bf16_t v) { return __uint_as_float(((unsigned)v) << 16); }
; DI float xhalf_sum(float v) { const auto r = __builtin_amdgcn_permlane32_swap(__float_as_uint(v), __float_as_uint(v), false, false); return __uint_as_float(r[0]) + __uint_as_float(r[1]); }
; DI bf16x8 pack8(const float* p) { u32x4 o; o.x = pk2h(p[0], p[1]); o.y = pk2h(p[2], p[3]); o.z = pk2h(p[4], p[5]); o.w = pk2h(p[6], p[7]); return __builtin_bit_cast(bf16x8, o); }
; DI void memattn_block(const Params& p, int layer, int bh, int tile4) {
;     ...
;     for (int ks = 0; ks < 8; ++ks) {
;       f32x4 a = (f32x4){0.f, 0.f, 0.f, 0.f}, c = a;
; #pragma unroll
;       for (int sp = 0; sp < 4; ++sp) { const bf16x8 r8 = *(const bf16x8*)(qp + (size_t)sp * M_ * 512 + ks * 16);
; #pragma unroll
;         for (int i = 0; i < 4; ++i) { a[i] += bf2f((bf16_t)r8[i]); c[i] += bf2f((bf16_t)r8[4 + i]); } }
;       a = a * rr; c = c * rr; qa[ks] = a; qb[ks] = c;
;       ss += (a[0] * a[0] + a[1] * a[1]) + (a[2] * a[2] + a[3] * a[3]) + (c[0] * c[0] + c[1] * c[1]) + (c[2] * c[2] + c[3] * c[3]);
;     }
;     ss = xhalf_sum(ss);
;     const float rs = rsqrtf(ss * (1.f / 128.f) + EPS_) * (ATTN_SCALE * LOG2E);
;     const float* gain = p.in[26] + layer * 128 + g * 8;
; #pragma unroll
;     for (int ks = 0; ks < 8; ++ks) {
;       const f32x4 g0 = *(const f32x4*)(gain + ks * 16), g1 = *(const f32x4*)(gain + ks * 16 + 4);
;       float v[8];
; #pragma unroll
;       for (int i = 0; i < 4; ++i) { v[i] = qa[ks][i] * rs * g0[i]; v[4 + i] = qb[ks][i] * rs * g1[i]; }
;       qf[ks] = pack8(v);
;     }
	v_and_b32_e32 v79, 0xffff0000, v2
	v_lshlrev_b32_e32 v78, 16, v2
	v_pk_add_f32 v[78:79], v[78:79], 0 op_sel_hi:[1,0]
	v_and_b32_e32 v81, 0xffff0000, v6
	v_lshlrev_b32_e32 v80, 16, v6
	v_pk_add_f32 v[78:79], v[78:79], v[80:81]
	v_and_b32_e32 v81, 0xffff0000, v10
	v_lshlrev_b32_e32 v80, 16, v10
	v_pk_add_f32 v[78:79], v[78:79], v[80:81]
	v_and_b32_e32 v81, 0xffff0000, v14
	v_lshlrev_b32_e32 v80, 16, v14
	v_pk_add_f32 v[80:81], v[78:79], v[80:81]
	v_and_b32_e32 v79, 0xffff0000, v4
	v_lshlrev_b32_e32 v78, 16, v4
	v_pk_add_f32 v[78:79], v[78:79], 0 op_sel_hi:[1,0]
	v_and_b32_e32 v85, 0xffff0000, v8
	v_lshlrev_b32_e32 v84, 16, v8
	v_pk_add_f32 v[78:79], v[78:79], v[84:85]
	v_and_b32_e32 v85, 0xffff0000, v12
	v_lshlrev_b32_e32 v84, 16, v12
	v_pk_add_f32 v[78:79], v[78:79], v[84:85]
	v_and_b32_e32 v85, 0xffff0000, v16
	v_lshlrev_b32_e32 v84, 16, v16
	v_pk_add_f32 v[84:85], v[78:79], v[84:85]
	v_and_b32_e32 v79, 0xffff0000, v3
	v_lshlrev_b32_e32 v78, 16, v3
	v_pk_add_f32 v[2:3], v[78:79], 0 op_sel_hi:[1,0]
	v_and_b32_e32 v79, 0xffff0000, v7
	v_lshlrev_b32_e32 v78, 16, v7
	v_pk_add_f32 v[2:3], v[2:3], v[78:79]
	v_and_b32_e32 v7, 0xffff0000, v11
	v_lshlrev_b32_e32 v6, 16, v11
	v_pk_add_f32 v[2:3], v[2:3], v[6:7]
	v_and_b32_e32 v7, 0xffff0000, v15
	v_lshlrev_b32_e32 v6, 16, v15
	v_pk_add_f32 v[2:3], v[2:3], v[6:7]
	v_and_b32_e32 v7, 0xffff0000, v5
	v_lshlrev_b32_e32 v6, 16, v5
	v_pk_add_f32 v[4:5], v[6:7], 0 op_sel_hi:[1,0]
	v_and_b32_e32 v7, 0xffff0000, v9
	v_lshlrev_b32_e32 v6, 16, v9
	v_pk_add_f32 v[4:5], v[4:5], v[6:7]
	v_and_b32_e32 v7, 0xffff0000, v13
	v_lshlrev_b32_e32 v6, 16, v13
	v_pk_add_f32 v[4:5], v[4:5], v[6:7]
	v_and_b32_e32 v7, 0xffff0000, v17
	v_lshlrev_b32_e32 v6, 16, v17
	v_pk_add_f32 v[4:5], v[4:5], v[6:7]
	v_pk_mul_f32 v[78:79], v[0:1], v[2:3] op_sel_hi:[0,1]
	v_pk_mul_f32 v[106:107], v[0:1], v[80:81] op_sel_hi:[0,1]
	v_pk_mul_f32 v[80:81], v[0:1], v[4:5] op_sel_hi:[0,1]
	global_load_dwordx4 v[2:5], v[36:37], off offset:224
	global_load_dwordx4 v[6:9], v[42:43], off offset:224
	global_load_dwordx4 v[10:13], v[40:41], off offset:224
	global_load_dwordx4 v[14:17], v[38:39], off offset:224
	v_pk_mul_f32 v[108:109], v[0:1], v[84:85] op_sel_hi:[0,1]
	s_waitcnt vmcnt(0)
	v_and_b32_e32 v37, 0xffff0000, v2
	v_lshlrev_b32_e32 v36, 16, v2
	v_pk_add_f32 v[36:37], v[36:37], 0 op_sel_hi:[1,0]
	v_and_b32_e32 v39, 0xffff0000, v6
	v_lshlrev_b32_e32 v38, 16, v6
	v_pk_add_f32 v[36:37], v[36:37], v[38:39]
	v_and_b32_e32 v39, 0xffff0000, v10
	v_lshlrev_b32_e32 v38, 16, v10
	v_pk_add_f32 v[36:37], v[36:37], v[38:39]
	v_and_b32_e32 v39, 0xffff0000, v14
	v_lshlrev_b32_e32 v38, 16, v14
	v_pk_add_f32 v[36:37], v[36:37], v[38:39]
	v_and_b32_e32 v39, 0xffff0000, v4
	v_lshlrev_b32_e32 v38, 16, v4
	v_pk_add_f32 v[38:39], v[38:39], 0 op_sel_hi:[1,0]
	v_and_b32_e32 v41, 0xffff0000, v8
	v_lshlrev_b32_e32 v40, 16, v8
	v_pk_add_f32 v[38:39], v[38:39], v[40:41]
	v_and_b32_e32 v41, 0xffff0000, v12
	v_lshlrev_b32_e32 v40, 16, v12
	v_pk_add_f32 v[38:39], v[38:39], v[40:41]
	v_and_b32_e32 v41, 0xffff0000, v16
	v_lshlrev_b32_e32 v40, 16, v16
	v_pk_add_f32 v[38:39], v[38:39], v[40:41]
	v_and_b32_e32 v41, 0xffff0000, v3
	v_lshlrev_b32_e32 v40, 16, v3
	v_pk_add_f32 v[2:3], v[40:41], 0 op_sel_hi:[1,0]
	v_and_b32_e32 v41, 0xffff0000, v7
	v_lshlrev_b32_e32 v40, 16, v7
	v_pk_add_f32 v[2:3], v[2:3], v[40:41]
	v_and_b32_e32 v7, 0xffff0000, v11
	v_lshlrev_b32_e32 v6, 16, v11
	v_pk_add_f32 v[2:3], v[2:3], v[6:7]
	v_and_b32_e32 v7, 0xffff0000, v15
	v_lshlrev_b32_e32 v6, 16, v15
	v_pk_add_f32 v[2:3], v[2:3], v[6:7]
	v_and_b32_e32 v7, 0xffff0000, v5
	v_lshlrev_b32_e32 v6, 16, v5
	v_pk_add_f32 v[4:5], v[6:7], 0 op_sel_hi:[1,0]
	v_and_b32_e32 v7, 0xffff0000, v9
	v_lshlrev_b32_e32 v6, 16, v9
	v_pk_add_f32 v[4:5], v[4:5], v[6:7]
	v_and_b32_e32 v7, 0xffff0000, v13
	v_lshlrev_b32_e32 v6, 16, v13
	v_pk_add_f32 v[4:5], v[4:5], v[6:7]
	v_and_b32_e32 v7, 0xffff0000, v17
	v_lshlrev_b32_e32 v6, 16, v17
	v_pk_add_f32 v[4:5], v[4:5], v[6:7]
	v_pk_mul_f32 v[14:15], v[0:1], v[36:37] op_sel_hi:[0,1]
	v_pk_mul_f32 v[10:11], v[0:1], v[4:5] op_sel_hi:[0,1]
	v_mov_b32_e32 v4, v109
	v_mov_b32_e32 v5, v15
	v_pk_mul_f32 v[12:13], v[0:1], v[2:3] op_sel_hi:[0,1]
	v_pk_mul_f32 v[16:17], v[0:1], v[38:39] op_sel_hi:[0,1]
	v_mov_b32_e32 v2, v108
	v_mov_b32_e32 v3, v14
	v_pk_mul_f32 v[4:5], v[4:5], v[4:5]
	v_mul_f32_e32 v0, v107, v107
	v_mul_f32_e32 v6, v12, v12
	v_pk_fma_f32 v[2:3], v[2:3], v[2:3], v[4:5]
	v_pk_fma_f32 v[4:5], v[106:107], v[106:107], v[0:1] op_sel_hi:[1,1,0]
	v_mul_f32_e32 v0, v79, v79
	v_mul_f32_e32 v8, v13, v13
	v_mov_b32_e32 v5, v6
	v_pk_fma_f32 v[6:7], v[78:79], v[78:79], v[0:1] op_sel_hi:[1,1,0]
	v_mul_f32_e32 v9, v10, v10
	v_mov_b32_e32 v7, v8
	v_pk_add_f32 v[4:5], v[4:5], v[6:7]
	v_mov_b32_e32 v6, v81
	v_mov_b32_e32 v7, v17
	v_pk_add_f32 v[2:3], v[2:3], v[4:5]
	v_mov_b32_e32 v4, v80
	v_mov_b32_e32 v5, v16
	v_pk_mul_f32 v[6:7], v[6:7], v[6:7]
	v_mul_f32_e32 v83, v11, v11
	v_pk_fma_f32 v[4:5], v[4:5], v[4:5], v[6:7]
	v_lshlrev_b32_e32 v6, 5, v114
	v_pk_add_f32 v[2:3], v[4:5], v[2:3]
	v_pk_add_f32 v[4:5], v[76:77], v[76:77] op_sel:[0,1] op_sel_hi:[1,0]
	s_nop 0
	v_mov_b32_e32 v5, v9
	v_pk_add_f32 v[4:5], v[4:5], v[82:83]
	s_nop 0
	v_pk_add_f32 v[2:3], v[4:5], v[2:3]
	s_nop 0
	v_pk_add_f32 v[2:3], v[2:3], v[2:3] op_sel:[0,1] op_sel_hi:[1,0]
	s_nop 0
	v_mov_b32_e32 v0, v2
	s_nop 1
	v_permlane32_swap_b32_e32 v2, v0
	v_add_f32_e32 v0, v2, v0
	v_fmamk_f32 v0, v0, 0x3c000000, v249
	v_cmp_gt_f32_e32 vcc, s22, v0
	v_mul_f32_e32 v2, 0x4b800000, v0
	s_nop 0
	v_cndmask_b32_e32 v0, v0, v2, vcc
	v_rsq_f32_e32 v0, v0
	s_nop 0
	v_mul_f32_e32 v2, 0x45800000, v0
	v_cndmask_b32_e32 v0, v0, v2, vcc
	global_load_dwordx4 v[200:203], v6, s[8:9] offset:16
	global_load_dwordx4 v[204:207], v6, s[8:9]
	global_load_dwordx4 v[208:211], v6, s[8:9] offset:80
	global_load_dwordx4 v[212:215], v6, s[8:9] offset:64
	global_load_dwordx4 v[216:219], v6, s[8:9] offset:144
	global_load_dwordx4 v[220:223], v6, s[8:9] offset:128
	global_load_dwordx4 v[224:227], v6, s[8:9] offset:208
	global_load_dwordx4 v[228:231], v6, s[8:9] offset:192
	global_load_dwordx4 v[232:235], v6, s[8:9] offset:272
	global_load_dwordx4 v[236:239], v6, s[8:9] offset:256
	global_load_dwordx4 v[240:243], v6, s[8:9] offset:336
	global_load_dwordx4 v[244:247], v6, s[8:9] offset:320
	global_load_dwordx4 v[156:159], v6, s[8:9] offset:400
	global_load_dwordx4 v[160:163], v6, s[8:9] offset:384
	global_load_dwordx4 v[164:167], v6, s[8:9] offset:464
	global_load_dwordx4 v[168:171], v6, s[8:9] offset:448
	v_mul_f32_e32 v0, 0x3e0293ee, v0
	v_pk_mul_f32 v[8:9], v[24:25], v[0:1] op_sel_hi:[1,0]
	v_pk_mul_f32 v[24:25], v[26:27], v[0:1] op_sel_hi:[1,0]
	v_pk_mul_f32 v[20:21], v[20:21], v[0:1] op_sel_hi:[1,0]
	v_pk_mul_f32 v[22:23], v[22:23], v[0:1] op_sel_hi:[1,0]
	v_pk_mul_f32 v[14:15], v[14:15], v[0:1] op_sel_hi:[1,0]
	v_pk_mul_f32 v[12:13], v[12:13], v[0:1] op_sel_hi:[1,0]
	v_pk_mul_f32 v[10:11], v[10:11], v[0:1] op_sel_hi:[1,0]
	s_waitcnt vmcnt(14)
; DI bf16x8 pack8(const float* p) { u32x4 o; o.x = pk2h(p[0], p[1]); o.y = pk2h(p[2], p[3]); o.z = pk2h(p[4], p[5]); o.w = pk2h(p[6], p[7]); return __builtin_bit_cast(bf16x8, o); }
; DI void memattn_block(const Params& p, int layer, int bh, int tile4) {
;     ...
; #pragma unroll
;     for (int ks = 0; ks < 8; ++ks) {
;       const f32x4 g0 = *(const f32x4*)(gain + ks * 16), g1 = *(const f32x4*)(gain + ks * 16 + 4);
;       float v[8];
; #pragma unroll
;       for (int i = 0; i < 4; ++i) { v[i] = qa[ks][i] * rs * g0[i]; v[4 + i] = qb[ks][i] * rs * g1[i]; }
;       qf[ks] = pack8(v);
;     }
	v_pk_mul_f32 v[2:3], v[200:201], v[24:25]
	v_pk_mul_f32 v[20:21], v[206:207], v[20:21]
	v_pk_mul_f32 v[4:5], v[202:203], v[22:23]
	v_cvt_pk_bf16_f32 v83, v20, v21
	v_cvt_pk_bf16_f32 v84, v2, v3
	v_cvt_pk_bf16_f32 v85, v4, v5
	v_pk_mul_f32 v[8:9], v[204:205], v[8:9]
	s_nop 0
	v_cvt_pk_bf16_f32 v82, v8, v9
	v_pk_mul_f32 v[8:9], v[32:33], v[0:1] op_sel_hi:[1,0]
	s_waitcnt vmcnt(12)
	v_pk_mul_f32 v[8:9], v[212:213], v[8:9]
	v_pk_mul_f32 v[20:21], v[34:35], v[0:1] op_sel_hi:[1,0]
	v_cvt_pk_bf16_f32 v86, v8, v9
	v_pk_mul_f32 v[2:3], v[208:209], v[20:21]
	v_pk_mul_f32 v[20:21], v[28:29], v[0:1] op_sel_hi:[1,0]
	v_cvt_pk_bf16_f32 v88, v2, v3
	v_pk_mul_f32 v[20:21], v[214:215], v[20:21]
	v_pk_mul_f32 v[22:23], v[30:31], v[0:1] op_sel_hi:[1,0]
	v_cvt_pk_bf16_f32 v87, v20, v21
	v_pk_mul_f32 v[4:5], v[210:211], v[22:23]
	v_pk_mul_f32 v[8:9], v[48:49], v[0:1] op_sel_hi:[1,0]
	v_cvt_pk_bf16_f32 v89, v4, v5
	s_waitcnt vmcnt(10)
	v_pk_mul_f32 v[8:9], v[220:221], v[8:9]
	v_pk_mul_f32 v[20:21], v[50:51], v[0:1] op_sel_hi:[1,0]
	v_cvt_pk_bf16_f32 v90, v8, v9
	v_pk_mul_f32 v[2:3], v[216:217], v[20:21]
	v_pk_mul_f32 v[20:21], v[44:45], v[0:1] op_sel_hi:[1,0]
	v_cvt_pk_bf16_f32 v92, v2, v3
	v_pk_mul_f32 v[20:21], v[222:223], v[20:21]
	v_pk_mul_f32 v[22:23], v[46:47], v[0:1] op_sel_hi:[1,0]
	v_cvt_pk_bf16_f32 v91, v20, v21
	v_pk_mul_f32 v[4:5], v[218:219], v[22:23]
	v_pk_mul_f32 v[8:9], v[56:57], v[0:1] op_sel_hi:[1,0]
	v_cvt_pk_bf16_f32 v93, v4, v5
	s_waitcnt vmcnt(8)
	v_pk_mul_f32 v[8:9], v[228:229], v[8:9]
	v_pk_mul_f32 v[20:21], v[58:59], v[0:1] op_sel_hi:[1,0]
	v_cvt_pk_bf16_f32 v94, v8, v9
	v_pk_mul_f32 v[2:3], v[224:225], v[20:21]
	v_pk_mul_f32 v[20:21], v[52:53], v[0:1] op_sel_hi:[1,0]
	v_cvt_pk_bf16_f32 v96, v2, v3
	v_pk_mul_f32 v[20:21], v[230:231], v[20:21]
	v_pk_mul_f32 v[22:23], v[54:55], v[0:1] op_sel_hi:[1,0]
	v_cvt_pk_bf16_f32 v95, v20, v21
	v_pk_mul_f32 v[4:5], v[226:227], v[22:23]
	v_pk_mul_f32 v[8:9], v[64:65], v[0:1] op_sel_hi:[1,0]
	v_cvt_pk_bf16_f32 v97, v4, v5
	s_waitcnt vmcnt(6)
	v_pk_mul_f32 v[8:9], v[236:237], v[8:9]
	v_pk_mul_f32 v[20:21], v[66:67], v[0:1] op_sel_hi:[1,0]
	v_cvt_pk_bf16_f32 v98, v8, v9
	v_pk_mul_f32 v[2:3], v[232:233], v[20:21]
	v_pk_mul_f32 v[20:21], v[60:61], v[0:1] op_sel_hi:[1,0]
	v_cvt_pk_bf16_f32 v100, v2, v3
	v_pk_mul_f32 v[20:21], v[238:239], v[20:21]
	v_pk_mul_f32 v[22:23], v[62:63], v[0:1] op_sel_hi:[1,0]
	v_cvt_pk_bf16_f32 v99, v20, v21
	v_pk_mul_f32 v[4:5], v[234:235], v[22:23]
	v_pk_mul_f32 v[8:9], v[72:73], v[0:1] op_sel_hi:[1,0]
	v_cvt_pk_bf16_f32 v101, v4, v5
	s_waitcnt vmcnt(4)
	v_pk_mul_f32 v[8:9], v[244:245], v[8:9]
	v_pk_mul_f32 v[20:21], v[74:75], v[0:1] op_sel_hi:[1,0]
	v_cvt_pk_bf16_f32 v102, v8, v9
	v_pk_mul_f32 v[2:3], v[20:21], v[240:241]
	v_pk_mul_f32 v[20:21], v[68:69], v[0:1] op_sel_hi:[1,0]
	v_cvt_pk_bf16_f32 v104, v2, v3
	v_pk_mul_f32 v[20:21], v[246:247], v[20:21]
	v_pk_mul_f32 v[22:23], v[70:71], v[0:1] op_sel_hi:[1,0]
	v_cvt_pk_bf16_f32 v103, v20, v21
	v_pk_mul_f32 v[4:5], v[22:23], v[242:243]
	v_pk_mul_f32 v[8:9], v[106:107], v[0:1] op_sel_hi:[1,0]
	v_cvt_pk_bf16_f32 v105, v4, v5
	s_waitcnt vmcnt(2)
	v_pk_mul_f32 v[8:9], v[8:9], v[160:161]
	v_pk_mul_f32 v[20:21], v[108:109], v[0:1] op_sel_hi:[1,0]
	v_cvt_pk_bf16_f32 v106, v8, v9
	v_pk_mul_f32 v[2:3], v[20:21], v[156:157]
	v_pk_mul_f32 v[20:21], v[78:79], v[0:1] op_sel_hi:[1,0]
	v_cvt_pk_bf16_f32 v108, v2, v3
	v_pk_mul_f32 v[20:21], v[20:21], v[162:163]
	v_pk_mul_f32 v[22:23], v[80:81], v[0:1] op_sel_hi:[1,0]
	v_cvt_pk_bf16_f32 v107, v20, v21
	v_pk_mul_f32 v[4:5], v[22:23], v[158:159]
	s_nop 0
	v_cvt_pk_bf16_f32 v109, v4, v5
	s_nop 0
	s_waitcnt vmcnt(0)
	v_pk_mul_f32 v[4:5], v[10:11], v[166:167]
	v_pk_mul_f32 v[6:7], v[14:15], v[168:169]
	v_pk_mul_f32 v[14:15], v[16:17], v[0:1] op_sel_hi:[1,0]
	v_pk_mul_f32 v[8:9], v[12:13], v[170:171]
	v_pk_mul_f32 v[2:3], v[14:15], v[164:165]
	v_cvt_pk_bf16_f32 v110, v6, v7
	v_cvt_pk_bf16_f32 v111, v8, v9
	v_cvt_pk_bf16_f32 v112, v2, v3
	v_cvt_pk_bf16_f32 v113, v4, v5

; #define NEG_INF (-__builtin_inff())
; DI float xhalf_max(float v) { const auto r = __builtin_amdgcn_permlane32_swap(__float_as_uint(v), __float_as_uint(v), false, false); return fmaxf(__uint_as_float(r[0]), __uint_as_float(r[1])); }
; DI float fexp2(float x) { return __builtin_amdgcn_exp2f(x); }
; DI f32x16 mfma32(bf16x8 a, bf16x8 b, f32x16 c) { return __builtin_amdgcn_mfma_f32_32x32x16_bf16(a, b, c, 0, 0, 0); }
; DI f32x16 zero16() { f32x16 z; for (int i = 0; i < 16; ++i) z[i] = 0.f; return z; }
; #define LAS __attribute__((address_space(3)))
; DI f32x16 score_tile_lds(const bf16x8 (&qf)[8], const LAS unsigned char* st, const LaneKV& L) {
;   f32x16 acc = zero16();
; #pragma unroll
;   for (int ks = 0; ks < 8; ++ks) { const bf16x8 a = *(const LAS bf16x8*)(st + L.kx + (((unsigned)ks ^ L.xh) << 5)); acc = mfma32(a, qf[ks], acc); }
;   return acc;
; }
; DI void softmax_step_lds(AttnState& st, float (&sc)[16], const LAS unsigned char* stv, const LaneKV& L) {
;   float mx = st.m;
; #pragma unroll
;   for (int i = 0; i < 16; ++i) mx = fmaxf(mx, sc[i]);
;   mx = xhalf_max(mx);
;   const float ms = (mx == NEG_INF) ? 0.f : mx;
;   if (__builtin_amdgcn_ballot_w64(mx > st.m) != 0ull) {
;     const float alpha = fexp2(st.m - ms);
;     st.l *= alpha;
; #pragma unroll
;     for (int vt = 0; vt < 4; ++vt)
; #pragma unroll
;       for (int i = 0; i < 16; ++i) st.o[vt][i] *= alpha;
;   }
.LBB0_108:
	v_add_u32_e32 v146, s13, v126
	v_add_u32_e32 v147, s13, v125
	v_add_u32_e32 v148, s13, v124
	v_add_u32_e32 v149, s13, v123
	v_add_u32_e32 v150, s13, v122
	v_add_u32_e32 v151, s13, v121
	v_add_u32_e32 v152, s13, v120
	v_add_u32_e32 v153, s13, v119
	ds_read_b128 v[172:175], v146
	ds_read_b128 v[176:179], v147
	ds_read_b128 v[180:183], v148
	ds_read_b128 v[184:187], v149
	ds_read_b128 v[220:223], v150
	ds_read_b128 v[224:227], v151
	ds_read_b128 v[228:231], v152
	ds_read_b128 v[232:235], v153
	s_mov_b32 s14, 0xff800000
	s_waitcnt lgkmcnt(7)
	v_mfma_f32_32x32x16_bf16 v[66:81], v[172:175], v[82:85], 0
	s_waitcnt lgkmcnt(6)
	v_mfma_f32_32x32x16_bf16 v[66:81], v[176:179], v[86:89], v[66:81]
	s_waitcnt lgkmcnt(5)
	v_mfma_f32_32x32x16_bf16 v[66:81], v[180:183], v[90:93], v[66:81]
	s_waitcnt lgkmcnt(4)
	v_mfma_f32_32x32x16_bf16 v[66:81], v[184:187], v[94:97], v[66:81]
	s_waitcnt lgkmcnt(3)
	v_mfma_f32_32x32x16_bf16 v[66:81], v[220:223], v[98:101], v[66:81]
	s_waitcnt lgkmcnt(2)
	v_mfma_f32_32x32x16_bf16 v[66:81], v[224:227], v[102:105], v[66:81]
	s_waitcnt lgkmcnt(1)
	v_mfma_f32_32x32x16_bf16 v[66:81], v[228:231], v[106:109], v[66:81]
	s_waitcnt lgkmcnt(0)
	v_mfma_f32_32x32x16_bf16 v[66:81], v[232:235], v[110:113], v[66:81]
	s_nop 11
	v_max3_f32 v128, v130, v66, v67
	v_max3_f32 v128, v128, v68, v69
	v_max3_f32 v128, v128, v70, v71
	v_max3_f32 v128, v128, v72, v73
	v_max3_f32 v128, v128, v74, v75
	v_max3_f32 v128, v128, v76, v77
	v_max3_f32 v128, v128, v78, v79
	v_max3_f32 v128, v128, v80, v81
	v_mov_b32_e32 v129, v128
	s_nop 1
	v_permlane32_swap_b32_e32 v128, v129
	v_max_f32_e32 v129, v129, v129
	v_max_f32_e32 v128, v128, v128
	v_max_f32_e32 v128, v128, v129
	v_cmp_neq_f32_e32 vcc, s14, v128
	s_nop 1
	v_cndmask_b32_e32 v129, 0, v128, vcc
	v_cmp_gt_f32_e32 vcc, v128, v130
	s_cbranch_vccz .LBB0_110
	v_sub_f32_e32 v130, v130, v129
	v_exp_f32_e32 v130, v130
	s_nop 0
	v_mul_f32_e32 v127, v127, v130
	v_pk_mul_f32 v[64:65], v[64:65], v[130:131] op_sel_hi:[1,0]
	v_pk_mul_f32 v[62:63], v[62:63], v[130:131] op_sel_hi:[1,0]
	v_pk_mul_f32 v[60:61], v[60:61], v[130:131] op_sel_hi:[1,0]
	v_pk_mul_f32 v[58:59], v[58:59], v[130:131] op_sel_hi:[1,0]
	v_pk_mul_f32 v[56:57], v[56:57], v[130:131] op_sel_hi:[1,0]
	v_pk_mul_f32 v[54:55], v[54:55], v[130:131] op_sel_hi:[1,0]
	v_pk_mul_f32 v[52:53], v[52:53], v[130:131] op_sel_hi:[1,0]
	v_pk_mul_f32 v[50:51], v[50:51], v[130:131] op_sel_hi:[1,0]
	v_pk_mul_f32 v[48:49], v[48:49], v[130:131] op_sel_hi:[1,0]
	v_pk_mul_f32 v[46:47], v[46:47], v[130:131] op_sel_hi:[1,0]
	v_pk_mul_f32 v[44:45], v[44:45], v[130:131] op_sel_hi:[1,0]
	v_pk_mul_f32 v[42:43], v[42:43], v[130:131] op_sel_hi:[1,0]
	v_pk_mul_f32 v[40:41], v[40:41], v[130:131] op_sel_hi:[1,0]
	v_pk_mul_f32 v[38:39], v[38:39], v[130:131] op_sel_hi:[1,0]
	v_pk_mul_f32 v[36:37], v[36:37], v[130:131] op_sel_hi:[1,0]
	v_pk_mul_f32 v[34:35], v[34:35], v[130:131] op_sel_hi:[1,0]
	v_pk_mul_f32 v[32:33], v[32:33], v[130:131] op_sel_hi:[1,0]
	v_pk_mul_f32 v[30:31], v[30:31], v[130:131] op_sel_hi:[1,0]
	v_pk_mul_f32 v[28:29], v[28:29], v[130:131] op_sel_hi:[1,0]
	v_pk_mul_f32 v[26:27], v[26:27], v[130:131] op_sel_hi:[1,0]
	v_pk_mul_f32 v[24:25], v[24:25], v[130:131] op_sel_hi:[1,0]
	v_pk_mul_f32 v[22:23], v[22:23], v[130:131] op_sel_hi:[1,0]
	v_pk_mul_f32 v[20:21], v[20:21], v[130:131] op_sel_hi:[1,0]
	v_pk_mul_f32 v[18:19], v[18:19], v[130:131] op_sel_hi:[1,0]
	v_pk_mul_f32 v[16:17], v[16:17], v[130:131] op_sel_hi:[1,0]
	v_pk_mul_f32 v[14:15], v[14:15], v[130:131] op_sel_hi:[1,0]
	v_pk_mul_f32 v[12:13], v[12:13], v[130:131] op_sel_hi:[1,0]
	v_pk_mul_f32 v[10:11], v[10:11], v[130:131] op_sel_hi:[1,0]
	v_pk_mul_f32 v[8:9], v[8:9], v[130:131] op_sel_hi:[1,0]
	v_pk_mul_f32 v[6:7], v[6:7], v[130:131] op_sel_hi:[1,0]
	v_pk_mul_f32 v[4:5], v[4:5], v[130:131] op_sel_hi:[1,0]
	v_pk_mul_f32 v[2:3], v[2:3], v[130:131] op_sel_hi:[1,0]
